# first grid sync: block 0 zeroes the barrier words and publishes a flag; every block polls the flag, then uses the same two-level barrier (runtime sync buffer no longer used)
# speedup vs baseline: 1.0024x; 1.0004x over previous
; __device__ __forceinline__ int ltid() { return launder((int)threadIdx.x); }
; __device__ __forceinline__ void prologue(const Params& P) {
;   unsigned char* ws = P.ws; const int tid = ltid();
;   if (blockIdx.x == 0 && tid < 64) {
;     unsigned* ctl = (unsigned*)(ws + WS_CTL);
;     if (tid < 8 || (tid >= 16 && tid < 48)) ctl[tid] = 0u;
_Z4mega6Params:
	s_load_dwordx16 s[4:19], s[0:1], 0x40
	s_add_u32 s56, s0, 0xa0
	s_load_dword s52, s[0:1], 0xa0
	s_addc_u32 s57, s1, 0
	v_and_b32_e32 v155, 0x3ff, v0
	s_waitcnt lgkmcnt(0)
	v_writelane_b32 v253, s4, 0
	v_mov_b32_e32 v4, v155
	s_cmp_eq_u32 s2, 0
	v_writelane_b32 v253, s5, 1
	v_writelane_b32 v253, s6, 2
	v_writelane_b32 v253, s7, 3
	v_writelane_b32 v253, s8, 4
	v_writelane_b32 v253, s9, 5
	v_writelane_b32 v253, s10, 6
	v_writelane_b32 v253, s11, 7
	v_writelane_b32 v253, s12, 8
	v_writelane_b32 v253, s13, 9
	v_writelane_b32 v253, s14, 10
	v_writelane_b32 v253, s15, 11
	v_writelane_b32 v253, s16, 12
	v_writelane_b32 v253, s17, 13
	v_writelane_b32 v253, s18, 14
	v_writelane_b32 v253, s19, 15
	s_load_dwordx8 s[4:11], s[0:1], 0x80
	s_mov_b32 s37, s2
	s_cselect_b64 s[2:3], -1, 0
	v_cmp_gt_i32_e32 vcc, 64, v4
	s_waitcnt lgkmcnt(0)
	v_writelane_b32 v253, s4, 16
	s_and_b64 s[2:3], s[2:3], vcc
	s_nop 0
	v_writelane_b32 v253, s5, 17
	v_writelane_b32 v253, s6, 18
	v_writelane_b32 v253, s7, 19
	v_writelane_b32 v253, s8, 20
	v_writelane_b32 v253, s9, 21
	v_writelane_b32 v253, s10, 22
	v_writelane_b32 v253, s11, 23
	s_and_saveexec_b64 s[4:5], s[2:3]
	s_cbranch_execz .LBB0_15
	v_add_u32_e32 v1, -16, v4
	v_cmp_lt_i32_e32 vcc, 7, v4
	v_cmp_lt_u32_e64 s[2:3], 31, v1
	s_and_b64 s[2:3], vcc, s[2:3]
	v_mov_b32_e32 v5, 0
	s_and_saveexec_b64 s[6:7], s[2:3]
	s_xor_b64 s[2:3], exec, s[6:7]
	s_or_saveexec_b64 s[2:3], s[2:3]
	v_mov_b64_e32 v[6:7], v[4:5]
	s_xor_b64 exec, exec, s[2:3]
	s_cbranch_execz .LBB0_3
	s_load_dwordx8 s[8:15], s[0:1], 0x80
	v_ashrrev_i32_e32 v7, 31, v4
	v_mov_b32_e32 v6, v4
	v_mov_b32_e32 v1, 0
	s_waitcnt lgkmcnt(0)
	v_lshl_add_u64 v[2:3], v[6:7], 2, s[14:15]
	global_store_dword v[2:3], v1, off
	s_waitcnt vmcnt(0)
	buffer_wbl2 sc1
	s_waitcnt vmcnt(0)
	v_mov_b32_e32 v2, 0x9e3779b9
	global_store_dword v1, v2, s[14:15] offset:192 sc0 sc1

; __global__ void __launch_bounds__(512) mega(Params P) {
;     ...
;   grid.sync();
.LBB0_208:
	s_or_b64 exec, exec, s[2:3]
	v_lshrrev_b32_e32 v1, 20, v0
	v_lshrrev_b32_e32 v0, 10, v0
	v_or_b32_e32 v0, v0, v1
	s_movk_i32 s0, 0x3ff
	v_and_or_b32 v0, v0, s0, v155
	s_barrier
	v_cmp_eq_u32_e64 s[2:3], 0, v0
	s_mov_b64 s[0:1], exec
	s_nop 0
	v_writelane_b32 v253, s2, 57
	s_nop 1
	v_writelane_b32 v253, s3, 58
	s_and_b64 s[2:3], s[0:1], s[2:3]
	s_mov_b64 exec, s[2:3]
	s_cbranch_execz .LBB0_218
	buffer_wbl2 sc1
	s_load_dwordx2 s[2:3], s[56:57], -0x8
	s_load_dword s4, s[56:57], 0x0
	v_readlane_b32 s5, v253, 55
	v_mov_b32_e32 v1, 0
	s_waitcnt lgkmcnt(0)
	s_waitcnt vmcnt(0)
.Lgb_flag:
	global_load_dword v0, v1, s[2:3] offset:192 sc1
	s_waitcnt vmcnt(0)
	v_cmp_eq_u32_e32 vcc, 0x9e3779b9, v0
	s_cbranch_vccnz .Lgb_flag_ok
	s_sleep 1
	s_branch .Lgb_flag
.Lgb_flag_ok:
	s_and_b32 s5, s5, 7
	s_add_i32 s6, s4, 7
	s_sub_i32 s6, s6, s5
	s_lshr_b32 s6, s6, 3
	s_min_u32 s7, s4, 8
	s_lshl_b32 s5, s5, 2
	s_addk_i32 s5, 0x88
	v_mov_b32_e32 v2, s5
	global_load_dword v0, v1, s[2:3] sc1
	v_mov_b32_e32 v3, 1
	s_waitcnt vmcnt(0)
	v_and_b32_e32 v0, 0xffff0000, v0
	global_atomic_add v3, v2, v3, s[2:3] sc0
	s_waitcnt vmcnt(0)
	v_and_b32_e32 v3, 0xffff, v3
	s_nop 0
	v_readfirstlane_b32 s5, v3
	s_nop 3
	s_add_i32 s8, s6, -1
	s_cmp_lg_u32 s5, s8
	s_cbranch_scc1 .Lgb_poll_8
	s_sub_i32 s5, 0x10000, s6
	v_mov_b32_e32 v3, s5
	global_atomic_add v3, v2, v3, s[2:3] sc0
	s_waitcnt vmcnt(0)
	v_mov_b32_e32 v3, 1
	global_atomic_add v3, v1, v3, s[2:3] sc0
	s_waitcnt vmcnt(0)
	v_and_b32_e32 v3, 0xffff, v3
	s_nop 0
	v_readfirstlane_b32 s5, v3
	s_nop 3
	s_add_i32 s8, s7, -1
	s_cmp_lg_u32 s5, s8
	s_cbranch_scc1 .Lgb_poll_8
	s_sub_i32 s5, 0x10000, s7
	v_mov_b32_e32 v3, s5
	global_atomic_add v1, v3, s[2:3]
.Lgb_poll_8:
	global_load_dword v3, v1, s[2:3] sc1
	s_waitcnt vmcnt(0)
	v_and_b32_e32 v3, 0xffff0000, v3
	v_cmp_ne_u32_e32 vcc, v3, v0
	s_cbranch_vccnz .Lgb_done_8
	s_sleep 1
	s_branch .Lgb_poll_8

; __device__ __forceinline__ int ltid() { return launder((int)threadIdx.x); }
; __device__ __forceinline__ void final_phase(const float* H, const float* g, float* out) {
;   const int lane = ltid() & 63, gw = blockIdx.x * 8 + (ltid() >> 6), nw = gridDim.x * 8;
;   f32x4 gv[4];
; #pragma unroll
;   for (int i = 0; i < 4; ++i) gv[i] = *(const f32x4*)(g + lane * 4 + 256 * i);
;   for (int row = gw; row < NREAL; row += 2 * nw) {
;     const int row2 = row + nw < NREAL ? row + nw : row;
;     const float* p = H + (size_t)row * DM + lane * 4; const float* p2 = H + (size_t)row2 * DM + lane * 4; f32x4 v[4], u[4]; float ss = 0.f, ss2 = 0.f;
.LBB0_1575:
	s_load_dwordx2 s[0:1], s[56:57], -0x8
	v_mov_b32_e32 v2, 0
	s_waitcnt lgkmcnt(0)
	global_store_dword v2, v2, s[0:1] offset:192
	v_mov_b32_e32 v0, v155
	v_readlane_b32 s0, v253, 56
	v_ashrrev_i32_e32 v1, 6, v155
	s_mov_b32 s5, 0x8000
	v_add_u32_e32 v22, s0, v1
	v_cmp_gt_i32_e32 vcc, s5, v22
	s_and_saveexec_b64 s[0:1], vcc
	v_readlane_b32 s16, v253, 59
	s_cbranch_execz .LBB0_1578
	v_lshlrev_b32_e32 v0, 4, v0
	v_readlane_b32 s8, v253, 16
	v_and_b32_e32 v18, 0x3f0, v0
	v_readlane_b32 s10, v253, 18
	v_readlane_b32 s11, v253, 19
	s_nop 4
	global_load_dwordx4 v[0:3], v18, s[10:11]
	global_load_dwordx4 v[4:7], v18, s[10:11] offset:1024
	global_load_dwordx4 v[8:11], v18, s[10:11] offset:2048
	global_load_dwordx4 v[12:15], v18, s[10:11] offset:3072
	v_readlane_b32 s9, v253, 17
	v_readlane_b32 s12, v253, 20
	v_readlane_b32 s13, v253, 21
	v_readlane_b32 s0, v253, 60
	s_mov_b64 s[6:7], s[10:11]
	s_mov_b64 s[8:9], s[12:13]
	v_mov_b32_e32 v19, 0
	v_readlane_b32 s1, v253, 61
	s_mov_b64 s[2:3], 0
	s_mov_b32 s4, 0x3a800000
	v_lshl_add_u64 v[16:17], s[0:1], 0, v[18:19]
	v_lshl_add_u64 v[18:19], s[8:9], 0, v[18:19]
	v_mov_b32_e32 v20, 0x358637bd
	s_mov_b32 s6, 0x800000
	s_movk_i32 s7, 0x7fff
	v_readlane_b32 s14, v253, 22
	v_readlane_b32 s15, v253, 23
